# GEMM accumulator zeroing with v_mov_b64 (64 instead of 128 moves per unit)
# speedup vs baseline: 1.0115x; 1.0114x over previous
; template <class Epi, class Sched, bool ALIGN_EPI = false, bool SP2 = false>
; __device__ __forceinline__ void gemm_phase(PG8_LAS unsigned char* lds, const Gemm g, const Sched& S, const Epi& E) {
;     ...
;         const char* nA = has_next ? (const char*)g.A + (size_t)nxt.pm * tstep : cA; const char* nB = has_next ? (const char*)g.Bt + (size_t)nxt.pn * tstep : cB;
;         for (int t = 0; t < nt; t += 2) {
;             const bool last = (t == nt - 2);
;             const char* a1 = cA + (size_t)(t + 1) * kstep;
;             const char* a2 = last ? nA : cA + (size_t)(t + 2) * kstep; const char* b2 = last ? nB : cB + (size_t)(t + 2) * kstep;
;     ...
;         for (int a = 0; a < 2; ++a)
; #pragma unroll
;             for (int b = 0; b < 2; ++b)
; #pragma unroll
;                 for (int m = 0; m < 4; ++m)
; #pragma unroll
;                     for (int n = 0; n < 2; ++n) acc[a][b][m][n] = (f32x4){0.f, 0.f, 0.f, 0.f};
.LBB0_127:
	s_ashr_i32 s27, s26, 31
	s_lshl_b64 s[28:29], s[26:27], 20
	s_add_u32 s28, s43, s28
	s_addc_u32 s29, s44, s29
	s_and_b64 s[30:31], s[6:7], exec
	s_cselect_b32 s27, s29, s35
	s_cselect_b32 s78, s28, s34
	s_ashr_i32 s25, s24, 31
	s_lshl_b64 s[30:31], s[24:25], 20
	s_add_u32 s30, s45, s30
	s_addc_u32 s31, s46, s31
	s_and_b64 s[40:41], s[6:7], exec
	s_cselect_b32 s25, s31, s9
	s_cselect_b32 s79, s30, s8
	s_add_u32 s80, s8, 0x100
	s_addc_u32 s81, s9, 0
	s_add_u32 s8, s34, 0x80080
	v_mov_b64_e32 v[6:7], 0
	v_mov_b64_e32 v[8:9], 0
	v_mov_b64_e32 v[10:11], 0
	v_mov_b64_e32 v[12:13], 0
	v_mov_b64_e32 v[14:15], 0
	v_mov_b64_e32 v[16:17], 0
	v_mov_b64_e32 v[18:19], 0
	v_mov_b64_e32 v[20:21], 0
	v_mov_b64_e32 v[22:23], 0
	v_mov_b64_e32 v[24:25], 0
	v_mov_b64_e32 v[26:27], 0
	v_mov_b64_e32 v[28:29], 0
	v_mov_b64_e32 v[30:31], 0
	v_mov_b64_e32 v[32:33], 0
	v_mov_b64_e32 v[34:35], 0
	v_mov_b64_e32 v[36:37], 0
	v_mov_b64_e32 v[38:39], 0
	v_mov_b64_e32 v[40:41], 0
	v_mov_b64_e32 v[42:43], 0
	v_mov_b64_e32 v[44:45], 0
	v_mov_b64_e32 v[46:47], 0
	v_mov_b64_e32 v[48:49], 0
	v_mov_b64_e32 v[50:51], 0
	v_mov_b64_e32 v[52:53], 0
	v_mov_b64_e32 v[54:55], 0
	v_mov_b64_e32 v[56:57], 0
	v_mov_b64_e32 v[58:59], 0
	v_mov_b64_e32 v[60:61], 0
	v_mov_b64_e32 v[62:63], 0
	v_mov_b64_e32 v[64:65], 0
	v_mov_b64_e32 v[66:67], 0
	v_mov_b64_e32 v[68:69], 0
	v_mov_b64_e32 v[70:71], 0
	v_mov_b64_e32 v[72:73], 0
	v_mov_b64_e32 v[74:75], 0
	v_mov_b64_e32 v[76:77], 0
	v_mov_b64_e32 v[78:79], 0
	v_mov_b64_e32 v[80:81], 0
	v_mov_b64_e32 v[82:83], 0
	v_mov_b64_e32 v[84:85], 0
	v_mov_b64_e32 v[86:87], 0
	v_mov_b64_e32 v[88:89], 0
	v_mov_b64_e32 v[90:91], 0
	v_mov_b64_e32 v[92:93], 0
	v_mov_b64_e32 v[94:95], 0
	v_mov_b64_e32 v[96:97], 0
	v_mov_b64_e32 v[98:99], 0
	v_mov_b64_e32 v[100:101], 0
	v_mov_b64_e32 v[102:103], 0
	v_mov_b64_e32 v[104:105], 0
	v_mov_b64_e32 v[106:107], 0
	v_mov_b64_e32 v[108:109], 0
	v_mov_b64_e32 v[110:111], 0
	v_mov_b64_e32 v[112:113], 0
	v_mov_b64_e32 v[114:115], 0
	v_mov_b64_e32 v[116:117], 0
	v_mov_b64_e32 v[118:119], 0
	v_mov_b64_e32 v[120:121], 0
	v_mov_b64_e32 v[122:123], 0
	v_mov_b64_e32 v[124:125], 0
	v_mov_b64_e32 v[126:127], 0
	v_mov_b64_e32 v[128:129], 0
	v_mov_b64_e32 v[130:131], 0
	v_mov_b64_e32 v[132:133], 0
	s_addc_u32 s9, s35, 0
	s_mov_b32 s82, -2

; template <class Epi, class Sched, bool ALIGN_EPI = false, bool SP2 = false>
; __device__ __forceinline__ void gemm_phase(PG8_LAS unsigned char* lds, const Gemm g, const Sched& S, const Epi& E) {
;     ...
;         for (int a = 0; a < 2; ++a)
; #pragma unroll
;             for (int b = 0; b < 2; ++b)
; #pragma unroll
;                 for (int m = 0; m < 4; ++m)
; #pragma unroll
;                     for (int n = 0; n < 2; ++n) acc[a][b][m][n] = (f32x4){0.f, 0.f, 0.f, 0.f};
.LBB0_234:
	s_add_u32 s81, s34, 0x100
	v_mov_b64_e32 v[6:7], 0
	v_mov_b64_e32 v[8:9], 0
	v_mov_b64_e32 v[10:11], 0
	v_mov_b64_e32 v[12:13], 0
	v_mov_b64_e32 v[14:15], 0
	v_mov_b64_e32 v[16:17], 0
	v_mov_b64_e32 v[18:19], 0
	v_mov_b64_e32 v[20:21], 0
	v_mov_b64_e32 v[22:23], 0
	v_mov_b64_e32 v[24:25], 0
	v_mov_b64_e32 v[26:27], 0
	v_mov_b64_e32 v[28:29], 0
	v_mov_b64_e32 v[30:31], 0
	v_mov_b64_e32 v[32:33], 0
	v_mov_b64_e32 v[34:35], 0
	v_mov_b64_e32 v[36:37], 0
	v_mov_b64_e32 v[38:39], 0
	v_mov_b64_e32 v[40:41], 0
	v_mov_b64_e32 v[42:43], 0
	v_mov_b64_e32 v[44:45], 0
	v_mov_b64_e32 v[46:47], 0
	v_mov_b64_e32 v[48:49], 0
	v_mov_b64_e32 v[66:67], 0
	v_mov_b64_e32 v[68:69], 0
	v_mov_b64_e32 v[70:71], 0
	v_mov_b64_e32 v[72:73], 0
	v_mov_b64_e32 v[74:75], 0
	v_mov_b64_e32 v[76:77], 0
	v_mov_b64_e32 v[78:79], 0
	v_mov_b64_e32 v[80:81], 0
	v_mov_b64_e32 v[82:83], 0
	v_mov_b64_e32 v[84:85], 0
	v_mov_b64_e32 v[86:87], 0
	v_mov_b64_e32 v[88:89], 0
	v_mov_b64_e32 v[90:91], 0
	v_mov_b64_e32 v[92:93], 0
	v_mov_b64_e32 v[94:95], 0
	v_mov_b64_e32 v[96:97], 0
	v_mov_b64_e32 v[98:99], 0
	v_mov_b64_e32 v[100:101], 0
	v_mov_b64_e32 v[102:103], 0
	v_mov_b64_e32 v[104:105], 0
	v_mov_b64_e32 v[106:107], 0
	v_mov_b64_e32 v[108:109], 0
	v_mov_b64_e32 v[110:111], 0
	v_mov_b64_e32 v[112:113], 0
	v_mov_b64_e32 v[114:115], 0
	v_mov_b64_e32 v[116:117], 0
	v_mov_b64_e32 v[118:119], 0
	v_mov_b64_e32 v[120:121], 0
	v_mov_b64_e32 v[122:123], 0
	v_mov_b64_e32 v[124:125], 0
	v_mov_b64_e32 v[126:127], 0
	v_mov_b64_e32 v[128:129], 0
	v_mov_b64_e32 v[130:131], 0
	v_mov_b64_e32 v[132:133], 0
	v_mov_b64_e32 v[134:135], 0
	v_mov_b64_e32 v[136:137], 0
	v_mov_b64_e32 v[138:139], 0
	v_mov_b64_e32 v[140:141], 0
	v_mov_b64_e32 v[142:143], 0
	v_mov_b64_e32 v[144:145], 0
	v_mov_b64_e32 v[146:147], 0
	v_mov_b64_e32 v[148:149], 0
	s_addc_u32 s82, s35, 0
	s_mov_b32 s83, -2
	s_waitcnt lgkmcnt(0)

; template <class Epi, class Sched, bool ALIGN_EPI = false, bool SP2 = false>
; __device__ __forceinline__ void gemm_phase(PG8_LAS unsigned char* lds, const Gemm g, const Sched& S, const Epi& E) {
;     ...
;         const char* nA = has_next ? (const char*)g.A + (size_t)nxt.pm * tstep : cA; const char* nB = has_next ? (const char*)g.Bt + (size_t)nxt.pn * tstep : cB;
;         for (int t = 0; t < nt; t += 2) {
;             const bool last = (t == nt - 2);
;             const char* a1 = cA + (size_t)(t + 1) * kstep;
;             const char* a2 = last ? nA : cA + (size_t)(t + 2) * kstep; const char* b2 = last ? nB : cB + (size_t)(t + 2) * kstep;
;     ...
;         for (int a = 0; a < 2; ++a)
; #pragma unroll
;             for (int b = 0; b < 2; ++b)
; #pragma unroll
;                 for (int m = 0; m < 4; ++m)
; #pragma unroll
;                     for (int n = 0; n < 2; ++n) acc[a][b][m][n] = (f32x4){0.f, 0.f, 0.f, 0.f};
.LBB0_395:
	s_ashr_i32 s23, s22, 31
	s_lshl_b64 s[24:25], s[22:23], 20
	s_add_u32 s24, s41, s24
	s_addc_u32 s25, s42, s25
	s_and_b64 s[26:27], s[8:9], exec
	s_cselect_b32 s23, s25, s31
	s_cselect_b32 s66, s24, s30
	s_ashr_i32 s21, s20, 31
	s_lshl_b64 s[26:27], s[20:21], 20
	s_add_u32 s26, s43, s26
	s_addc_u32 s27, s44, s27
	s_and_b64 s[34:35], s[8:9], exec
	s_cselect_b32 s21, s27, s11
	s_cselect_b32 s67, s26, s10
	s_add_u32 s69, s10, 0x100
	s_addc_u32 s70, s11, 0
	s_add_u32 s10, s30, 0x80080
	v_mov_b64_e32 v[6:7], 0
	v_mov_b64_e32 v[8:9], 0
	v_mov_b64_e32 v[10:11], 0
	v_mov_b64_e32 v[12:13], 0
	v_mov_b64_e32 v[14:15], 0
	v_mov_b64_e32 v[16:17], 0
	v_mov_b64_e32 v[18:19], 0
	v_mov_b64_e32 v[20:21], 0
	v_mov_b64_e32 v[22:23], 0
	v_mov_b64_e32 v[24:25], 0
	v_mov_b64_e32 v[26:27], 0
	v_mov_b64_e32 v[28:29], 0
	v_mov_b64_e32 v[30:31], 0
	v_mov_b64_e32 v[32:33], 0
	v_mov_b64_e32 v[34:35], 0
	v_mov_b64_e32 v[36:37], 0
	v_mov_b64_e32 v[38:39], 0
	v_mov_b64_e32 v[40:41], 0
	v_mov_b64_e32 v[42:43], 0
	v_mov_b64_e32 v[44:45], 0
	v_mov_b64_e32 v[46:47], 0
	v_mov_b64_e32 v[48:49], 0
	v_mov_b64_e32 v[50:51], 0
	v_mov_b64_e32 v[52:53], 0
	v_mov_b64_e32 v[54:55], 0
	v_mov_b64_e32 v[56:57], 0
	v_mov_b64_e32 v[58:59], 0
	v_mov_b64_e32 v[60:61], 0
	v_mov_b64_e32 v[62:63], 0
	v_mov_b64_e32 v[64:65], 0
	v_mov_b64_e32 v[66:67], 0
	v_mov_b64_e32 v[68:69], 0
	v_mov_b64_e32 v[70:71], 0
	v_mov_b64_e32 v[72:73], 0
	v_mov_b64_e32 v[74:75], 0
	v_mov_b64_e32 v[76:77], 0
	v_mov_b64_e32 v[78:79], 0
	v_mov_b64_e32 v[80:81], 0
	v_mov_b64_e32 v[82:83], 0
	v_mov_b64_e32 v[84:85], 0
	v_mov_b64_e32 v[86:87], 0
	v_mov_b64_e32 v[88:89], 0
	v_mov_b64_e32 v[90:91], 0
	v_mov_b64_e32 v[92:93], 0
	v_mov_b64_e32 v[94:95], 0
	v_mov_b64_e32 v[96:97], 0
	v_mov_b64_e32 v[98:99], 0
	v_mov_b64_e32 v[100:101], 0
	v_mov_b64_e32 v[102:103], 0
	v_mov_b64_e32 v[104:105], 0
	v_mov_b64_e32 v[106:107], 0
	v_mov_b64_e32 v[108:109], 0
	v_mov_b64_e32 v[110:111], 0
	v_mov_b64_e32 v[112:113], 0
	v_mov_b64_e32 v[114:115], 0
	v_mov_b64_e32 v[116:117], 0
	v_mov_b64_e32 v[118:119], 0
	v_mov_b64_e32 v[120:121], 0
	v_mov_b64_e32 v[122:123], 0
	v_mov_b64_e32 v[124:125], 0
	v_mov_b64_e32 v[126:127], 0
	v_mov_b64_e32 v[128:129], 0
	v_mov_b64_e32 v[130:131], 0
	v_mov_b64_e32 v[132:133], 0
	s_addc_u32 s11, s31, 0
	s_mov_b32 s71, -2

; template <class Epi, class Sched, bool ALIGN_EPI = false, bool SP2 = false>
; __device__ __forceinline__ void gemm_phase(PG8_LAS unsigned char* lds, const Gemm g, const Sched& S, const Epi& E) {
;     ...
;         const char* nA = has_next ? (const char*)g.A + (size_t)nxt.pm * tstep : cA; const char* nB = has_next ? (const char*)g.Bt + (size_t)nxt.pn * tstep : cB;
;         for (int t = 0; t < nt; t += 2) {
;             const bool last = (t == nt - 2);
;             const char* a1 = cA + (size_t)(t + 1) * kstep;
;             const char* a2 = last ? nA : cA + (size_t)(t + 2) * kstep; const char* b2 = last ? nB : cB + (size_t)(t + 2) * kstep;
;     ...
;         for (int a = 0; a < 2; ++a)
; #pragma unroll
;             for (int b = 0; b < 2; ++b)
; #pragma unroll
;                 for (int m = 0; m < 4; ++m)
; #pragma unroll
;                     for (int n = 0; n < 2; ++n) acc[a][b][m][n] = (f32x4){0.f, 0.f, 0.f, 0.f};
.LBB0_817:
	s_ashr_i32 s21, s20, 31
	s_lshl_b64 s[22:23], s[20:21], 19
	s_add_u32 s22, s0, s22
	s_addc_u32 s23, s1, s23
	s_and_b64 s[24:25], s[8:9], exec
	s_cselect_b32 s21, s23, s31
	s_cselect_b32 s66, s22, s30
	s_ashr_i32 s19, s18, 31
	s_lshl_b64 s[24:25], s[18:19], 19
	s_add_u32 s24, s42, s24
	s_addc_u32 s25, s43, s25
	s_and_b64 s[34:35], s[8:9], exec
	s_cselect_b32 s19, s25, s27
	s_cselect_b32 s67, s24, s26
	s_add_u32 s69, s26, 0x100
	s_addc_u32 s70, s27, 0
	s_add_u32 s26, s30, 0x40080
	v_mov_b64_e32 v[6:7], 0
	v_mov_b64_e32 v[8:9], 0
	v_mov_b64_e32 v[10:11], 0
	v_mov_b64_e32 v[12:13], 0
	v_mov_b64_e32 v[14:15], 0
	v_mov_b64_e32 v[16:17], 0
	v_mov_b64_e32 v[18:19], 0
	v_mov_b64_e32 v[20:21], 0
	v_mov_b64_e32 v[22:23], 0
	v_mov_b64_e32 v[24:25], 0
	v_mov_b64_e32 v[26:27], 0
	v_mov_b64_e32 v[28:29], 0
	v_mov_b64_e32 v[30:31], 0
	v_mov_b64_e32 v[32:33], 0
	v_mov_b64_e32 v[34:35], 0
	v_mov_b64_e32 v[36:37], 0
	v_mov_b64_e32 v[38:39], 0
	v_mov_b64_e32 v[40:41], 0
	v_mov_b64_e32 v[42:43], 0
	v_mov_b64_e32 v[44:45], 0
	v_mov_b64_e32 v[46:47], 0
	v_mov_b64_e32 v[48:49], 0
	v_mov_b64_e32 v[50:51], 0
	v_mov_b64_e32 v[52:53], 0
	v_mov_b64_e32 v[54:55], 0
	v_mov_b64_e32 v[56:57], 0
	v_mov_b64_e32 v[58:59], 0
	v_mov_b64_e32 v[60:61], 0
	v_mov_b64_e32 v[62:63], 0
	v_mov_b64_e32 v[64:65], 0
	v_mov_b64_e32 v[66:67], 0
	v_mov_b64_e32 v[68:69], 0
	v_mov_b64_e32 v[70:71], 0
	v_mov_b64_e32 v[72:73], 0
	v_mov_b64_e32 v[74:75], 0
	v_mov_b64_e32 v[76:77], 0
	v_mov_b64_e32 v[78:79], 0
	v_mov_b64_e32 v[80:81], 0
	v_mov_b64_e32 v[82:83], 0
	v_mov_b64_e32 v[84:85], 0
	v_mov_b64_e32 v[86:87], 0
	v_mov_b64_e32 v[88:89], 0
	v_mov_b64_e32 v[90:91], 0
	v_mov_b64_e32 v[92:93], 0
	v_mov_b64_e32 v[94:95], 0
	v_mov_b64_e32 v[96:97], 0
	v_mov_b64_e32 v[98:99], 0
	v_mov_b64_e32 v[100:101], 0
	v_mov_b64_e32 v[102:103], 0
	v_mov_b64_e32 v[104:105], 0
	v_mov_b64_e32 v[106:107], 0
	v_mov_b64_e32 v[108:109], 0
	v_mov_b64_e32 v[110:111], 0
	v_mov_b64_e32 v[112:113], 0
	v_mov_b64_e32 v[114:115], 0
	v_mov_b64_e32 v[116:117], 0
	v_mov_b64_e32 v[118:119], 0
	v_mov_b64_e32 v[120:121], 0
	v_mov_b64_e32 v[122:123], 0
	v_mov_b64_e32 v[124:125], 0
	v_mov_b64_e32 v[126:127], 0
	v_mov_b64_e32 v[128:129], 0
	v_mov_b64_e32 v[130:131], 0
	v_mov_b64_e32 v[132:133], 0
	s_addc_u32 s27, s31, 0
	s_mov_b32 s71, -2

; template <class Epi, class Sched, bool ALIGN_EPI = false, bool SP2 = false>
; __device__ __forceinline__ void gemm_phase(PG8_LAS unsigned char* lds, const Gemm g, const Sched& S, const Epi& E) {
;     ...
;         const char* nA = has_next ? (const char*)g.A + (size_t)nxt.pm * tstep : cA; const char* nB = has_next ? (const char*)g.Bt + (size_t)nxt.pn * tstep : cB;
;         for (int t = 0; t < nt; t += 2) {
;             const bool last = (t == nt - 2);
;             const char* a1 = cA + (size_t)(t + 1) * kstep;
;             const char* a2 = last ? nA : cA + (size_t)(t + 2) * kstep; const char* b2 = last ? nB : cB + (size_t)(t + 2) * kstep;
;     ...
;         for (int a = 0; a < 2; ++a)
; #pragma unroll
;             for (int b = 0; b < 2; ++b)
; #pragma unroll
;                 for (int m = 0; m < 4; ++m)
; #pragma unroll
;                     for (int n = 0; n < 2; ++n) acc[a][b][m][n] = (f32x4){0.f, 0.f, 0.f, 0.f};
.LBB0_904:
	s_ashr_i32 s21, s20, 31
	v_cmp_lt_i64_e32 vcc, s[22:23], v[154:155]
	s_lshl_b64 s[22:23], s[20:21], 20
	s_add_u32 s22, s44, s22
	s_addc_u32 s23, s45, s23
	s_and_b64 s[24:25], vcc, exec
	s_cselect_b32 s21, s23, s27
	s_cselect_b32 s78, s22, s26
	s_ashr_i32 s19, s18, 31
	s_lshl_b64 s[24:25], s[18:19], 20
	s_add_u32 s24, s46, s24
	s_addc_u32 s25, s47, s25
	s_and_b64 s[34:35], vcc, exec
	s_cselect_b32 s19, s25, s31
	s_cselect_b32 s79, s24, s30
	s_add_u32 s80, s30, 0x100
	v_mov_b64_e32 v[6:7], 0
	v_mov_b64_e32 v[8:9], 0
	v_mov_b64_e32 v[10:11], 0
	v_mov_b64_e32 v[12:13], 0
	v_mov_b64_e32 v[14:15], 0
	v_mov_b64_e32 v[16:17], 0
	v_mov_b64_e32 v[18:19], 0
	v_mov_b64_e32 v[20:21], 0
	v_mov_b64_e32 v[22:23], 0
	v_mov_b64_e32 v[24:25], 0
	v_mov_b64_e32 v[26:27], 0
	v_mov_b64_e32 v[28:29], 0
	v_mov_b64_e32 v[30:31], 0
	v_mov_b64_e32 v[32:33], 0
	v_mov_b64_e32 v[34:35], 0
	v_mov_b64_e32 v[36:37], 0
	v_mov_b64_e32 v[38:39], 0
	v_mov_b64_e32 v[40:41], 0
	v_mov_b64_e32 v[42:43], 0
	v_mov_b64_e32 v[44:45], 0
	v_mov_b64_e32 v[46:47], 0
	v_mov_b64_e32 v[48:49], 0
	v_mov_b64_e32 v[50:51], 0
	v_mov_b64_e32 v[52:53], 0
	v_mov_b64_e32 v[54:55], 0
	v_mov_b64_e32 v[56:57], 0
	v_mov_b64_e32 v[58:59], 0
	v_mov_b64_e32 v[60:61], 0
	v_mov_b64_e32 v[62:63], 0
	v_mov_b64_e32 v[64:65], 0
	v_mov_b64_e32 v[66:67], 0
	v_mov_b64_e32 v[68:69], 0
	v_mov_b64_e32 v[70:71], 0
	v_mov_b64_e32 v[72:73], 0
	v_mov_b64_e32 v[74:75], 0
	v_mov_b64_e32 v[76:77], 0
	v_mov_b64_e32 v[82:83], 0
	v_mov_b64_e32 v[84:85], 0
	v_mov_b64_e32 v[90:91], 0
	v_mov_b64_e32 v[92:93], 0
	v_mov_b64_e32 v[102:103], 0
	v_mov_b64_e32 v[104:105], 0
	v_mov_b64_e32 v[106:107], 0
	v_mov_b64_e32 v[108:109], 0
	v_mov_b64_e32 v[110:111], 0
	v_mov_b64_e32 v[112:113], 0
	v_mov_b64_e32 v[114:115], 0
	v_mov_b64_e32 v[116:117], 0
	v_mov_b64_e32 v[118:119], 0
	v_mov_b64_e32 v[120:121], 0
	v_mov_b64_e32 v[122:123], 0
	v_mov_b64_e32 v[124:125], 0
	v_mov_b64_e32 v[126:127], 0
	v_mov_b64_e32 v[128:129], 0
	v_mov_b64_e32 v[130:131], 0
	v_mov_b64_e32 v[132:133], 0
	v_mov_b64_e32 v[134:135], 0
	v_mov_b64_e32 v[136:137], 0
	v_mov_b64_e32 v[138:139], 0
	v_mov_b64_e32 v[140:141], 0
	v_mov_b64_e32 v[142:143], 0
	v_mov_b64_e32 v[144:145], 0
	v_mov_b64_e32 v[146:147], 0
	v_mov_b64_e32 v[148:149], 0
	s_mov_b32 s54, s83
	s_addc_u32 s81, s31, 0
	s_mov_b32 s82, -2
	s_waitcnt lgkmcnt(0)

; template <class Epi, class Sched, bool ALIGN_EPI = false, bool SP2 = false>
; __device__ __forceinline__ void gemm_phase(PG8_LAS unsigned char* lds, const Gemm g, const Sched& S, const Epi& E) {
;     ...
;         const char* nA = has_next ? (const char*)g.A + (size_t)nxt.pm * tstep : cA; const char* nB = has_next ? (const char*)g.Bt + (size_t)nxt.pn * tstep : cB;
;         for (int t = 0; t < nt; t += 2) {
;             const bool last = (t == nt - 2);
;             const char* a1 = cA + (size_t)(t + 1) * kstep;
;             const char* a2 = last ? nA : cA + (size_t)(t + 2) * kstep; const char* b2 = last ? nB : cB + (size_t)(t + 2) * kstep;
;     ...
;         for (int a = 0; a < 2; ++a)
; #pragma unroll
;             for (int b = 0; b < 2; ++b)
; #pragma unroll
;                 for (int m = 0; m < 4; ++m)
; #pragma unroll
;                     for (int n = 0; n < 2; ++n) acc[a][b][m][n] = (f32x4){0.f, 0.f, 0.f, 0.f};
.LBB0_1015:
	s_ashr_i32 s17, s16, 31
	s_lshl_b64 s[18:19], s[16:17], 20
	s_add_u32 s18, s31, s18
	s_addc_u32 s19, s34, s19
	s_and_b64 s[20:21], s[6:7], exec
	s_cselect_b32 s17, s19, s25
	s_cselect_b32 s50, s18, s24
	s_ashr_i32 s15, s14, 31
	s_lshl_b64 s[20:21], s[14:15], 20
	s_add_u32 s20, s35, s20
	s_addc_u32 s21, s40, s21
	s_and_b64 s[26:27], s[6:7], exec
	s_cselect_b32 s15, s21, s23
	s_cselect_b32 s51, s20, s22
	s_add_u32 s52, s22, 0x100
	s_addc_u32 s53, s23, 0
	s_add_u32 s22, s24, 0x80080
	v_mov_b64_e32 v[6:7], 0
	v_mov_b64_e32 v[8:9], 0
	v_mov_b64_e32 v[10:11], 0
	v_mov_b64_e32 v[12:13], 0
	v_mov_b64_e32 v[14:15], 0
	v_mov_b64_e32 v[16:17], 0
	v_mov_b64_e32 v[18:19], 0
	v_mov_b64_e32 v[20:21], 0
	v_mov_b64_e32 v[22:23], 0
	v_mov_b64_e32 v[24:25], 0
	v_mov_b64_e32 v[26:27], 0
	v_mov_b64_e32 v[28:29], 0
	v_mov_b64_e32 v[30:31], 0
	v_mov_b64_e32 v[32:33], 0
	v_mov_b64_e32 v[34:35], 0
	v_mov_b64_e32 v[36:37], 0
	v_mov_b64_e32 v[38:39], 0
	v_mov_b64_e32 v[40:41], 0
	v_mov_b64_e32 v[42:43], 0
	v_mov_b64_e32 v[44:45], 0
	v_mov_b64_e32 v[46:47], 0
	v_mov_b64_e32 v[48:49], 0
	v_mov_b64_e32 v[50:51], 0
	v_mov_b64_e32 v[52:53], 0
	v_mov_b64_e32 v[54:55], 0
	v_mov_b64_e32 v[56:57], 0
	v_mov_b64_e32 v[58:59], 0
	v_mov_b64_e32 v[60:61], 0
	v_mov_b64_e32 v[62:63], 0
	v_mov_b64_e32 v[64:65], 0
	v_mov_b64_e32 v[66:67], 0
	v_mov_b64_e32 v[68:69], 0
	v_mov_b64_e32 v[70:71], 0
	v_mov_b64_e32 v[72:73], 0
	v_mov_b64_e32 v[74:75], 0
	v_mov_b64_e32 v[76:77], 0
	v_mov_b64_e32 v[78:79], 0
	v_mov_b64_e32 v[80:81], 0
	v_mov_b64_e32 v[82:83], 0
	v_mov_b64_e32 v[84:85], 0
	v_mov_b64_e32 v[86:87], 0
	v_mov_b64_e32 v[88:89], 0
	v_mov_b64_e32 v[90:91], 0
	v_mov_b64_e32 v[92:93], 0
	v_mov_b64_e32 v[94:95], 0
	v_mov_b64_e32 v[96:97], 0
	v_mov_b64_e32 v[98:99], 0
	v_mov_b64_e32 v[100:101], 0
	v_mov_b64_e32 v[102:103], 0
	v_mov_b64_e32 v[104:105], 0
	v_mov_b64_e32 v[106:107], 0
	v_mov_b64_e32 v[108:109], 0
	v_mov_b64_e32 v[110:111], 0
	v_mov_b64_e32 v[112:113], 0
	v_mov_b64_e32 v[114:115], 0
	v_mov_b64_e32 v[116:117], 0
	v_mov_b64_e32 v[118:119], 0
	v_mov_b64_e32 v[120:121], 0
	v_mov_b64_e32 v[122:123], 0
	v_mov_b64_e32 v[124:125], 0
	v_mov_b64_e32 v[126:127], 0
	v_mov_b64_e32 v[128:129], 0
	v_mov_b64_e32 v[130:131], 0
	v_mov_b64_e32 v[132:133], 0
	s_addc_u32 s23, s25, 0
	s_mov_b32 s66, -2

; template <class Epi, class Sched, bool ALIGN_EPI = false, bool SP2 = false>
; __device__ __forceinline__ void gemm_phase(PG8_LAS unsigned char* lds, const Gemm g, const Sched& S, const Epi& E) {
;     ...
;         const char* nA = has_next ? (const char*)g.A + (size_t)nxt.pm * tstep : cA; const char* nB = has_next ? (const char*)g.Bt + (size_t)nxt.pn * tstep : cB;
;         for (int t = 0; t < nt; t += 2) {
;             const bool last = (t == nt - 2);
;             const char* a1 = cA + (size_t)(t + 1) * kstep;
;             const char* a2 = last ? nA : cA + (size_t)(t + 2) * kstep; const char* b2 = last ? nB : cB + (size_t)(t + 2) * kstep;
;     ...
;         for (int a = 0; a < 2; ++a)
; #pragma unroll
;             for (int b = 0; b < 2; ++b)
; #pragma unroll
;                 for (int m = 0; m < 4; ++m)
; #pragma unroll
;                     for (int n = 0; n < 2; ++n) acc[a][b][m][n] = (f32x4){0.f, 0.f, 0.f, 0.f};
.LBB0_1629:
	s_ashr_i32 s19, s18, 31
	v_cmp_lt_i64_e32 vcc, s[20:21], v[154:155]
	s_lshl_b64 s[20:21], s[18:19], 20
	s_add_u32 s20, s40, s20
	s_addc_u32 s21, s41, s21
	s_and_b64 s[22:23], vcc, exec
	s_cselect_b32 s19, s21, s25
	s_cselect_b32 s66, s20, s24
	s_ashr_i32 s17, s16, 31
	s_lshl_b64 s[22:23], s[16:17], 20
	s_add_u32 s22, s42, s22
	s_addc_u32 s23, s43, s23
	s_and_b64 s[28:29], vcc, exec
	s_cselect_b32 s17, s23, s27
	s_cselect_b32 s67, s22, s26
	s_add_u32 s69, s26, 0x100
	v_mov_b64_e32 v[6:7], 0
	v_mov_b64_e32 v[8:9], 0
	v_mov_b64_e32 v[10:11], 0
	v_mov_b64_e32 v[12:13], 0
	v_mov_b64_e32 v[14:15], 0
	v_mov_b64_e32 v[16:17], 0
	v_mov_b64_e32 v[18:19], 0
	v_mov_b64_e32 v[20:21], 0
	v_mov_b64_e32 v[22:23], 0
	v_mov_b64_e32 v[24:25], 0
	v_mov_b64_e32 v[26:27], 0
	v_mov_b64_e32 v[28:29], 0
	v_mov_b64_e32 v[30:31], 0
	v_mov_b64_e32 v[32:33], 0
	v_mov_b64_e32 v[34:35], 0
	v_mov_b64_e32 v[36:37], 0
	v_mov_b64_e32 v[38:39], 0
	v_mov_b64_e32 v[40:41], 0
	v_mov_b64_e32 v[42:43], 0
	v_mov_b64_e32 v[44:45], 0
	v_mov_b64_e32 v[46:47], 0
	v_mov_b64_e32 v[48:49], 0
	v_mov_b64_e32 v[50:51], 0
	v_mov_b64_e32 v[52:53], 0
	v_mov_b64_e32 v[54:55], 0
	v_mov_b64_e32 v[56:57], 0
	v_mov_b64_e32 v[58:59], 0
	v_mov_b64_e32 v[60:61], 0
	v_mov_b64_e32 v[62:63], 0
	v_mov_b64_e32 v[64:65], 0
	v_mov_b64_e32 v[66:67], 0
	v_mov_b64_e32 v[68:69], 0
	v_mov_b64_e32 v[70:71], 0
	v_mov_b64_e32 v[72:73], 0
	v_mov_b64_e32 v[74:75], 0
	v_mov_b64_e32 v[76:77], 0
	v_mov_b64_e32 v[82:83], 0
	v_mov_b64_e32 v[84:85], 0
	v_mov_b64_e32 v[86:87], 0
	v_mov_b64_e32 v[88:89], 0
	v_mov_b64_e32 v[102:103], 0
	v_mov_b64_e32 v[104:105], 0
	v_mov_b64_e32 v[106:107], 0
	v_mov_b64_e32 v[108:109], 0
	v_mov_b64_e32 v[110:111], 0
	v_mov_b64_e32 v[112:113], 0
	v_mov_b64_e32 v[114:115], 0
	v_mov_b64_e32 v[116:117], 0
	v_mov_b64_e32 v[118:119], 0
	v_mov_b64_e32 v[120:121], 0
	v_mov_b64_e32 v[122:123], 0
	v_mov_b64_e32 v[124:125], 0
	v_mov_b64_e32 v[126:127], 0
	v_mov_b64_e32 v[128:129], 0
	v_mov_b64_e32 v[130:131], 0
	v_mov_b64_e32 v[132:133], 0
	v_mov_b64_e32 v[134:135], 0
	v_mov_b64_e32 v[136:137], 0
	v_mov_b64_e32 v[138:139], 0
	v_mov_b64_e32 v[140:141], 0
	v_mov_b64_e32 v[142:143], 0
	v_mov_b64_e32 v[144:145], 0
	v_mov_b64_e32 v[146:147], 0
	v_mov_b64_e32 v[148:149], 0
	s_mov_b32 s54, s83
	s_addc_u32 s70, s27, 0
	s_mov_b32 s71, -2
	s_waitcnt lgkmcnt(0)
